# mixer epilogue: row-sum atomics pre-reduced over the 4 column waves through LDS (2 atomics per wave per unit instead of 8); on top of v41
# baseline (speedup 1.0000x reference)
.Lxr2_3:
.LBB0_1073:
	v_mul_f32_e32 v88, v192, v192
	v_mul_f32_e32 v89, v190, v190
	v_fmac_f32_e32 v88, v193, v193
	v_fmac_f32_e32 v89, v191, v191
	v_add_f32_e32 v88, v89, v88
	v_mul_f32_e32 v89, v174, v174
	v_mul_f32_e32 v96, v177, v177
	v_fmac_f32_e32 v89, v175, v175
	v_fmac_f32_e32 v96, v176, v176
	v_add_f32_e32 v89, v96, v89
	v_add_f32_e32 v88, v89, v88
	v_mul_f32_e32 v89, v198, v198
	v_mul_f32_e32 v96, v194, v194
	v_fmac_f32_e32 v89, v199, v199
	v_fmac_f32_e32 v96, v195, v195
	v_add_f32_e32 v89, v96, v89
	v_mul_f32_e32 v96, v110, v110
	v_mul_f32_e32 v97, v113, v113
	v_fmac_f32_e32 v96, v111, v111
	v_fmac_f32_e32 v97, v112, v112
	v_add_f32_e32 v96, v97, v96
	v_add_f32_e32 v89, v96, v89
	v_add_f32_e32 v96, v88, v89
	v_lshl_add_u64 v[88:89], v[226:227], 0, v[120:121]
	s_waitcnt vmcnt(0)
	v_pk_fma_f32 v[26:27], v[26:27], v[74:75], v[62:63]
	v_lshlrev_b64 v[62:63], 1, v[88:89]
	v_pk_fma_f32 v[32:33], v[32:33], v[80:81], v[60:61]
	v_pk_fma_f32 v[30:31], v[30:31], v[78:79], v[58:59]
	v_pk_fma_f32 v[28:29], v[28:29], v[76:77], v[64:65]
	v_cvt_pk_bf16_f32 v58, v30, v31
	v_cvt_pk_bf16_f32 v59, v32, v33
	v_lshl_add_u64 v[64:65], s[12:13], 0, v[62:63]
	v_cvt_pk_bf16_f32 v60, v26, v27
	v_cvt_pk_bf16_f32 v61, v28, v29
	v_lshl_add_u64 v[62:63], s[18:19], 0, v[62:63]
	v_pk_mul_f32 v[64:65], v[68:69], v[28:29]
	v_pk_mul_f32 v[58:59], v[70:71], v[30:31]
	v_pk_mul_f32 v[60:61], v[72:73], v[32:33]
	v_cvt_pk_bf16_f32 v58, v58, v59
	v_pk_mul_f32 v[88:89], v[66:67], v[26:27]
	v_cvt_pk_bf16_f32 v59, v60, v61
	v_pk_fma_f32 v[18:19], v[18:19], v[74:75], v[54:55]
	v_cvt_pk_bf16_f32 v60, v88, v89
	v_cvt_pk_bf16_f32 v61, v64, v65
	flat_store_dwordx4 v[62:63], v[58:61]
	v_pk_fma_f32 v[24:25], v[24:25], v[80:81], v[52:53]
	v_pk_fma_f32 v[22:23], v[22:23], v[78:79], v[50:51]
	v_lshl_add_u64 v[58:59], v[228:229], 0, v[120:121]
	v_lshlrev_b64 v[54:55], 1, v[58:59]
	v_pk_fma_f32 v[20:21], v[20:21], v[76:77], v[56:57]
	v_cvt_pk_bf16_f32 v50, v22, v23
	v_cvt_pk_bf16_f32 v51, v24, v25
	v_lshl_add_u64 v[56:57], s[12:13], 0, v[54:55]
	v_cvt_pk_bf16_f32 v52, v18, v19
	v_cvt_pk_bf16_f32 v53, v20, v21
	v_lshl_add_u64 v[54:55], s[18:19], 0, v[54:55]
	v_pk_mul_f32 v[56:57], v[68:69], v[20:21]
	v_pk_mul_f32 v[50:51], v[70:71], v[22:23]
	v_pk_mul_f32 v[52:53], v[72:73], v[24:25]
	v_cvt_pk_bf16_f32 v50, v50, v51
	v_pk_mul_f32 v[58:59], v[66:67], v[18:19]
	v_cvt_pk_bf16_f32 v51, v52, v53
	v_pk_fma_f32 v[10:11], v[10:11], v[74:75], v[46:47]
	v_cvt_pk_bf16_f32 v52, v58, v59
	v_cvt_pk_bf16_f32 v53, v56, v57
	flat_store_dwordx4 v[54:55], v[50:53]
	v_pk_fma_f32 v[16:17], v[16:17], v[80:81], v[44:45]
	v_pk_fma_f32 v[14:15], v[14:15], v[78:79], v[42:43]
	v_lshl_add_u64 v[50:51], v[230:231], 0, v[120:121]
	v_lshlrev_b64 v[46:47], 1, v[50:51]
	v_pk_fma_f32 v[12:13], v[12:13], v[76:77], v[48:49]
	v_cvt_pk_bf16_f32 v42, v14, v15
	v_cvt_pk_bf16_f32 v43, v16, v17
	v_lshl_add_u64 v[48:49], s[12:13], 0, v[46:47]
	v_cvt_pk_bf16_f32 v44, v10, v11
	v_cvt_pk_bf16_f32 v45, v12, v13
	v_lshl_add_u64 v[46:47], s[18:19], 0, v[46:47]
	v_pk_mul_f32 v[48:49], v[68:69], v[12:13]
	v_pk_mul_f32 v[42:43], v[70:71], v[14:15]
	v_pk_mul_f32 v[44:45], v[72:73], v[16:17]
	v_cvt_pk_bf16_f32 v42, v42, v43
	v_pk_mul_f32 v[50:51], v[66:67], v[10:11]
	v_cvt_pk_bf16_f32 v43, v44, v45
	v_pk_fma_f32 v[2:3], v[2:3], v[74:75], v[38:39]
	v_cvt_pk_bf16_f32 v44, v50, v51
	v_cvt_pk_bf16_f32 v45, v48, v49
	flat_store_dwordx4 v[46:47], v[42:45]
	v_pk_fma_f32 v[8:9], v[8:9], v[80:81], v[36:37]
	v_pk_fma_f32 v[6:7], v[6:7], v[78:79], v[34:35]
	v_lshl_add_u64 v[42:43], v[128:129], 0, v[120:121]
	v_lshlrev_b64 v[38:39], 1, v[42:43]
	v_pk_fma_f32 v[4:5], v[4:5], v[76:77], v[40:41]
	v_cvt_pk_bf16_f32 v34, v6, v7
	v_cvt_pk_bf16_f32 v35, v8, v9
	v_cvt_pk_bf16_f32 v36, v2, v3
	v_lshl_add_u64 v[40:41], s[12:13], 0, v[38:39]
	v_cvt_pk_bf16_f32 v37, v4, v5
	v_pk_mul_f32 v[42:43], v[66:67], v[2:3]
	v_lshl_add_u64 v[38:39], s[18:19], 0, v[38:39]
	v_pk_mul_f32 v[36:37], v[72:73], v[8:9]
	v_pk_mul_f32 v[34:35], v[70:71], v[6:7]
	v_pk_mul_f32 v[40:41], v[68:69], v[4:5]
	v_cvt_pk_bf16_f32 v34, v34, v35
	v_cvt_pk_bf16_f32 v35, v36, v37
	v_cvt_pk_bf16_f32 v36, v42, v43
	ds_swizzle_b32 v42, v96 offset:swizzle(SWAP,16)
	v_cvt_pk_bf16_f32 v37, v40, v41
	flat_store_dwordx4 v[38:39], v[34:37]
	s_lshl_b32 s96, s72, 5
	s_lshr_b32 s97, s82, 3
	s_add_i32 s96, s96, s97
	s_add_i32 s96, s96, 0x20000
	v_and_b32_e32 v246, 15, v178
	v_lshl_add_u32 v246, v246, 4, s96
	v_cmp_eq_u32_e32 vcc, 0, v245
	s_waitcnt lgkmcnt(0)
	v_add_f32_e32 v36, v96, v42
	v_mov_b32_e32 v37, v36
	s_nop 1
	v_permlane32_swap_b32_e32 v36, v37
	v_lshl_add_u64 v[34:35], v[178:179], 3, s[20:21]
	s_and_saveexec_b64 s[30:31], vcc
	s_cbranch_execz .LBB0_1075
	v_add_f32_e32 v36, v36, v37
	ds_write_b32 v246, v36
.LBB0_1075:
	s_or_b64 exec, exec, s[30:31]
	v_mul_f32_e32 v36, v172, v172
	v_mul_f32_e32 v37, v170, v170
	v_fmac_f32_e32 v36, v173, v173
	v_fmac_f32_e32 v37, v171, v171
	v_add_f32_e32 v36, v37, v36
	v_mul_f32_e32 v37, v166, v166
	v_mul_f32_e32 v38, v169, v169
	v_fmac_f32_e32 v37, v167, v167
	v_fmac_f32_e32 v38, v168, v168
	v_add_f32_e32 v37, v38, v37
	v_add_f32_e32 v36, v37, v36
	v_mul_f32_e32 v37, v108, v108
	v_mul_f32_e32 v38, v106, v106
	v_fmac_f32_e32 v37, v109, v109
	v_fmac_f32_e32 v38, v107, v107
	v_add_f32_e32 v37, v38, v37
	v_mul_f32_e32 v38, v102, v102
	v_mul_f32_e32 v39, v105, v105
	v_fmac_f32_e32 v38, v103, v103
	v_fmac_f32_e32 v39, v104, v104
	v_add_f32_e32 v38, v39, v38
	v_add_f32_e32 v37, v38, v37
	v_add_f32_e32 v36, v36, v37
	ds_swizzle_b32 v37, v36 offset:swizzle(SWAP,16)
	s_waitcnt lgkmcnt(0)
	v_add_f32_e32 v36, v36, v37
	v_mov_b32_e32 v37, v36
	s_nop 1
	v_permlane32_swap_b32_e32 v36, v37
	s_and_saveexec_b64 s[30:31], vcc
	s_cbranch_execz .LBB0_1077
	v_add_f32_e32 v36, v36, v37
	ds_write_b32 v246, v36 offset:256
.LBB0_1077:
	s_or_b64 exec, exec, s[30:31]
	v_mul_f32_e32 v36, v164, v164
	v_mul_f32_e32 v37, v162, v162
	v_fmac_f32_e32 v36, v165, v165
	v_fmac_f32_e32 v37, v163, v163
	v_add_f32_e32 v36, v37, v36
	v_mul_f32_e32 v37, v158, v158
	v_mul_f32_e32 v38, v157, v157
	v_fmac_f32_e32 v37, v159, v159
	v_fmac_f32_e32 v38, v156, v156
	v_add_f32_e32 v37, v38, v37
	v_add_f32_e32 v36, v37, v36
	v_mul_f32_e32 v37, v100, v100
	v_mul_f32_e32 v38, v98, v98
	v_fmac_f32_e32 v37, v101, v101
	v_fmac_f32_e32 v38, v99, v99
	v_add_f32_e32 v37, v38, v37
	v_mul_f32_e32 v38, v94, v94
	v_mul_f32_e32 v39, v93, v93
	v_fmac_f32_e32 v38, v95, v95
	v_fmac_f32_e32 v39, v92, v92
	v_add_f32_e32 v38, v39, v38
	v_add_f32_e32 v37, v38, v37
	v_add_f32_e32 v36, v36, v37
	ds_swizzle_b32 v37, v36 offset:swizzle(SWAP,16)
	s_waitcnt lgkmcnt(0)
	v_add_f32_e32 v36, v36, v37
	v_mov_b32_e32 v37, v36
	s_nop 1
	v_permlane32_swap_b32_e32 v36, v37
	s_and_saveexec_b64 s[30:31], vcc
	s_cbranch_execz .LBB0_1079
	v_add_f32_e32 v36, v36, v37
	ds_write_b32 v246, v36 offset:512
.LBB0_1079:
	s_or_b64 exec, exec, s[30:31]
	v_mul_f32_e32 v36, v154, v154
	v_mul_f32_e32 v37, v148, v148
	v_fmac_f32_e32 v36, v155, v155
	v_fmac_f32_e32 v37, v149, v149
	v_add_f32_e32 v36, v37, v36
	v_mul_f32_e32 v37, v150, v150
	v_mul_f32_e32 v38, v147, v147
	v_fmac_f32_e32 v37, v151, v151
	v_fmac_f32_e32 v38, v146, v146
	v_add_f32_e32 v37, v38, v37
	v_add_f32_e32 v36, v37, v36
	v_mul_f32_e32 v37, v90, v90
	v_mul_f32_e32 v38, v84, v84
	v_fmac_f32_e32 v37, v91, v91
	v_fmac_f32_e32 v38, v85, v85
	v_add_f32_e32 v37, v38, v37
	v_mul_f32_e32 v38, v86, v86
	v_mul_f32_e32 v39, v83, v83
	v_fmac_f32_e32 v38, v87, v87
	v_fmac_f32_e32 v39, v82, v82
	v_add_f32_e32 v38, v39, v38
	v_add_f32_e32 v37, v38, v37
	v_add_f32_e32 v36, v36, v37
	ds_swizzle_b32 v37, v36 offset:swizzle(SWAP,16)
	s_waitcnt lgkmcnt(0)
	v_add_f32_e32 v36, v36, v37
	v_mov_b32_e32 v37, v36
	s_nop 1
	v_permlane32_swap_b32_e32 v36, v37
	s_and_saveexec_b64 s[30:31], vcc
	s_cbranch_execz .LBB0_1081
	v_add_f32_e32 v36, v36, v37
	ds_write_b32 v246, v36 offset:768
.LBB0_1081:
	s_or_b64 exec, exec, s[30:31]
	v_mul_f32_e32 v36, v152, v152
	v_mul_f32_e32 v37, v140, v140
	v_fmac_f32_e32 v36, v153, v153
	v_fmac_f32_e32 v37, v141, v141
	v_mul_f32_e32 v30, v30, v30
	v_mul_f32_e32 v26, v26, v26
	v_add_f32_e32 v36, v37, v36
	v_mul_f32_e32 v37, v144, v144
	v_mul_f32_e32 v38, v139, v139
	v_fmac_f32_e32 v30, v31, v31
	v_mul_f32_e32 v31, v32, v32
	v_fmac_f32_e32 v26, v27, v27
	v_mul_f32_e32 v27, v29, v29
	v_fmac_f32_e32 v37, v145, v145
	v_fmac_f32_e32 v38, v138, v138
	v_fmac_f32_e32 v31, v33, v33
	v_fmac_f32_e32 v27, v28, v28
	v_add_f32_e32 v37, v38, v37
	v_add_f32_e32 v30, v31, v30
	v_add_f32_e32 v26, v27, v26
	v_add_f32_e32 v36, v37, v36
	v_add_f32_e32 v26, v26, v30
	v_add_f32_e32 v26, v36, v26
	ds_swizzle_b32 v27, v26 offset:swizzle(SWAP,16)
	s_waitcnt lgkmcnt(0)
	v_add_f32_e32 v26, v26, v27
	v_mov_b32_e32 v27, v26
	s_nop 1
	v_permlane32_swap_b32_e32 v26, v27
	s_and_saveexec_b64 s[30:31], vcc
	s_cbranch_execz .LBB0_1083
	v_add_f32_e32 v26, v26, v27
	ds_write_b32 v246, v26 offset:1024
.LBB0_1083:
	s_or_b64 exec, exec, s[30:31]
	v_mul_f32_e32 v26, v160, v160
	v_mul_f32_e32 v27, v142, v142
	v_fmac_f32_e32 v26, v161, v161
	v_fmac_f32_e32 v27, v143, v143
	v_mul_f32_e32 v22, v22, v22
	v_mul_f32_e32 v18, v18, v18
	v_add_f32_e32 v26, v27, v26
	v_mul_f32_e32 v27, v134, v134
	v_mul_f32_e32 v28, v137, v137
	v_fmac_f32_e32 v22, v23, v23
	v_mul_f32_e32 v23, v24, v24
	v_fmac_f32_e32 v18, v19, v19
	v_mul_f32_e32 v19, v21, v21
	v_fmac_f32_e32 v27, v135, v135
	v_fmac_f32_e32 v28, v136, v136
	v_fmac_f32_e32 v23, v25, v25
	v_fmac_f32_e32 v19, v20, v20
	v_add_f32_e32 v27, v28, v27
	v_add_f32_e32 v22, v23, v22
	v_add_f32_e32 v18, v19, v18
	v_add_f32_e32 v26, v27, v26
	v_add_f32_e32 v18, v18, v22
	v_add_f32_e32 v18, v26, v18
	ds_swizzle_b32 v19, v18 offset:swizzle(SWAP,16)
	s_waitcnt lgkmcnt(0)
	v_add_f32_e32 v18, v18, v19
	v_mov_b32_e32 v19, v18
	s_nop 1
	v_permlane32_swap_b32_e32 v18, v19
	s_and_saveexec_b64 s[30:31], vcc
	s_cbranch_execz .LBB0_1085
	v_add_f32_e32 v18, v18, v19
	ds_write_b32 v246, v18 offset:1280
.LBB0_1085:
	s_or_b64 exec, exec, s[30:31]
	v_mul_f32_e32 v18, v132, v132
	v_mul_f32_e32 v19, v130, v130
	v_fmac_f32_e32 v18, v133, v133
	v_fmac_f32_e32 v19, v131, v131
	v_mul_f32_e32 v14, v14, v14
	v_mul_f32_e32 v10, v10, v10
	v_add_f32_e32 v18, v19, v18
	v_mul_f32_e32 v19, v126, v126
	v_mul_f32_e32 v20, v125, v125
	v_fmac_f32_e32 v14, v15, v15
	v_mul_f32_e32 v15, v16, v16
	v_fmac_f32_e32 v10, v11, v11
	v_mul_f32_e32 v11, v13, v13
	v_fmac_f32_e32 v19, v127, v127
	v_fmac_f32_e32 v20, v124, v124
	v_fmac_f32_e32 v15, v17, v17
	v_fmac_f32_e32 v11, v12, v12
	v_add_f32_e32 v19, v20, v19
	v_add_f32_e32 v14, v15, v14
	v_add_f32_e32 v10, v11, v10
	v_add_f32_e32 v18, v19, v18
	v_add_f32_e32 v10, v10, v14
	v_add_f32_e32 v10, v18, v10
	ds_swizzle_b32 v11, v10 offset:swizzle(SWAP,16)
	s_waitcnt lgkmcnt(0)
	v_add_f32_e32 v10, v10, v11
	v_mov_b32_e32 v11, v10
	s_nop 1
	v_permlane32_swap_b32_e32 v10, v11
	s_and_saveexec_b64 s[30:31], vcc
	s_cbranch_execz .LBB0_1087
	v_add_f32_e32 v10, v10, v11
	ds_write_b32 v246, v10 offset:1536
.LBB0_1087:
	s_or_b64 exec, exec, s[30:31]
	v_mul_f32_e32 v10, v122, v122
	v_mul_f32_e32 v11, v116, v116
	v_fmac_f32_e32 v10, v123, v123
	v_fmac_f32_e32 v11, v117, v117
	v_mul_f32_e32 v6, v6, v6
	v_mul_f32_e32 v2, v2, v2
	v_add_f32_e32 v10, v11, v10
	v_mul_f32_e32 v11, v118, v118
	v_mul_f32_e32 v12, v115, v115
	v_fmac_f32_e32 v6, v7, v7
	v_mul_f32_e32 v7, v8, v8
	v_fmac_f32_e32 v2, v3, v3
	v_mul_f32_e32 v3, v5, v5
	v_fmac_f32_e32 v11, v119, v119
	v_fmac_f32_e32 v12, v114, v114
	v_fmac_f32_e32 v7, v9, v9
	v_fmac_f32_e32 v3, v4, v4
	v_add_f32_e32 v11, v12, v11
	v_add_f32_e32 v6, v7, v6
	v_add_f32_e32 v2, v3, v2
	v_add_f32_e32 v10, v11, v10
	v_add_f32_e32 v2, v2, v6
	v_add_f32_e32 v2, v10, v2
	ds_swizzle_b32 v3, v2 offset:swizzle(SWAP,16)
	s_waitcnt lgkmcnt(0)
	v_add_f32_e32 v2, v2, v3
	v_mov_b32_e32 v3, v2
	s_nop 1
	v_permlane32_swap_b32_e32 v2, v3
	s_and_saveexec_b64 s[8:9], vcc
	s_cbranch_execz .LBB0_1089
	v_add_f32_e32 v2, v2, v3
	ds_write_b32 v246, v2 offset:1792
.LBB0_1089:
	s_or_b64 exec, exec, s[8:9]
	s_waitcnt lgkmcnt(0)
	s_barrier
	s_lshl_b32 s97, s82, 4
	s_lshl_b32 s96, s72, 5
	s_add_i32 s96, s96, s97
	s_add_i32 s96, s96, 0x20000
	v_and_b32_e32 v247, 15, v178
	v_lshl_add_u32 v247, v247, 4, s96
	ds_read_b128 v[36:39], v247
	ds_read_b128 v[40:43], v247 offset:256
	s_lshr_b32 s96, s82, 6
	s_lshl_b32 s96, s96, 10
	s_bfe_u32 s97, s82, 0x10005
	s_lshl_b32 s97, s97, 8
	s_add_i32 s96, s96, s97
	s_mov_b32 s97, 0
	v_lshl_add_u64 v[44:45], v[34:35], 0, s[96:97]
	s_waitcnt lgkmcnt(0)
	v_add_f32_e32 v36, v36, v37
	v_add_f32_e32 v38, v38, v39
	v_add_f32_e32 v36, v36, v38
	v_add_f32_e32 v40, v40, v41
	v_add_f32_e32 v42, v42, v43
	v_add_f32_e32 v40, v40, v42
	s_and_saveexec_b64 s[30:31], vcc
	v_mul_f32_e32 v36, 0x49800000, v36
	v_trunc_f32_e32 v36, v36
	v_mul_f32_e64 v37, |v36|, s78
	v_floor_f32_e32 v37, v37
	v_fma_f32 v38, v37, s74, |v36|
	v_cvt_u32_f32_e32 v38, v38
	v_cvt_u32_f32_e32 v37, v37
	v_ashrrev_i32_e32 v39, 31, v36
	v_xor_b32_e32 v36, v38, v39
	v_xor_b32_e32 v37, v37, v39
	v_sub_co_u32_e64 v36, s[8:9], v36, v39
	s_nop 1
	v_subb_co_u32_e64 v37, s[8:9], v37, v39, s[8:9]
	global_atomic_add_x2 v[44:45], v[36:37], off
	v_mul_f32_e32 v40, 0x49800000, v40
	v_trunc_f32_e32 v40, v40
	v_mul_f32_e64 v41, |v40|, s78
	v_floor_f32_e32 v41, v41
	v_fma_f32 v42, v41, s74, |v40|
	v_cvt_u32_f32_e32 v42, v42
	v_cvt_u32_f32_e32 v41, v41
	v_ashrrev_i32_e32 v43, 31, v40
	v_xor_b32_e32 v40, v42, v43
	v_xor_b32_e32 v41, v41, v43
	v_sub_co_u32_e64 v40, s[8:9], v40, v43
	s_nop 1
	v_subb_co_u32_e64 v41, s[8:9], v41, v43, s[8:9]
	global_atomic_add_x2 v[44:45], v[40:41], off offset:128
	s_or_b64 exec, exec, s[30:31]
	s_and_b64 vcc, exec, s[6:7]
	s_mov_b64 s[6:7], -1
	s_cbranch_vccnz .LBB0_1034
	s_and_b64 vcc, exec, s[2:3]
	s_cbranch_vccnz .LBB0_1033
	s_barrier
	s_branch .LBB0_1033
